# FFN-up SwiGLU epilogue: 8 independent element chains interleaved (same ops and order per element), no s_nop padding
# speedup vs baseline: 1.0072x; 1.0072x over previous
.LBB0_1206:
	s_add_u32 s28, s22, 0xfffc0080
	s_addc_u32 s29, s23, -1
	s_add_i32 s84, 0, 0x10000
	v_add_u32_e32 v140, s84, v143
	ds_read_b128 v[146:149], v140
	ds_read_b128 v[150:153], v140 offset:1024
	ds_read_b128 v[154:157], v140 offset:2048
	ds_read_b128 v[158:161], v140 offset:3072
	s_cmp_eq_u32 s83, 12
	s_cselect_b32 s35, s13, s29
	s_cselect_b32 s34, s79, s28
	s_cselect_b32 s29, s11, s82
	s_cselect_b32 s28, s80, s81
	v_lshl_add_u64 v[140:141], s[22:23], 0, v[136:137]
	s_add_i32 m0, s19, 0xc000
	ds_read_b128 v[162:165], v145
	ds_read_b128 v[166:169], v145 offset:1024
	ds_read_b128 v[170:173], v145 offset:2048
	ds_read_b128 v[174:177], v145 offset:3072
	ds_read_b128 v[178:181], v145 offset:4096
	ds_read_b128 v[182:185], v145 offset:5120
	ds_read_b128 v[186:189], v145 offset:6144
	ds_read_b128 v[190:193], v145 offset:7168
	global_load_lds_dwordx4 v[140:141], off
	v_lshl_add_u64 v[140:141], s[22:23], 0, v[138:139]
	s_add_i32 m0, s19, 0xe000
	s_nop 0
	global_load_lds_dwordx4 v[140:141], off
	s_waitcnt lgkmcnt(8)
	s_barrier
	s_waitcnt lgkmcnt(0)
	s_setprio 1
	s_waitcnt lgkmcnt(0)
	v_mfma_f32_16x16x32_bf16 v[126:129], v[146:149], v[162:165], v[126:129]
	v_mfma_f32_16x16x32_bf16 v[118:121], v[154:157], v[162:165], v[118:121]
	v_mfma_f32_16x16x32_bf16 v[110:113], v[146:149], v[170:173], v[110:113]
	v_mfma_f32_16x16x32_bf16 v[102:105], v[154:157], v[170:173], v[102:105]
	v_mfma_f32_16x16x32_bf16 v[94:97], v[146:149], v[178:181], v[94:97]
	v_mfma_f32_16x16x32_bf16 v[86:89], v[154:157], v[178:181], v[86:89]
	v_mfma_f32_16x16x32_bf16 v[78:81], v[146:149], v[186:189], v[78:81]
	v_mfma_f32_16x16x32_bf16 v[70:73], v[154:157], v[186:189], v[70:73]
	v_mfma_f32_16x16x32_bf16 v[126:129], v[150:153], v[166:169], v[126:129]
	v_mfma_f32_16x16x32_bf16 v[118:121], v[158:161], v[166:169], v[118:121]
	v_mfma_f32_16x16x32_bf16 v[110:113], v[150:153], v[174:177], v[110:113]
	v_mfma_f32_16x16x32_bf16 v[102:105], v[158:161], v[174:177], v[102:105]
	v_mfma_f32_16x16x32_bf16 v[94:97], v[150:153], v[182:185], v[94:97]
	v_mfma_f32_16x16x32_bf16 v[86:89], v[158:161], v[182:185], v[86:89]
	v_mfma_f32_16x16x32_bf16 v[78:81], v[150:153], v[190:193], v[78:81]
	v_mfma_f32_16x16x32_bf16 v[70:73], v[158:161], v[190:193], v[70:73]
	s_setprio 0
	s_barrier
	s_add_i32 s86, 0, 0x14000
	v_add_u32_e32 v140, s86, v143
	s_add_i32 s84, s84, s63
	ds_read_b128 v[194:197], v140
	ds_read_b128 v[198:201], v140 offset:1024
	ds_read_b128 v[202:205], v140 offset:2048
	ds_read_b128 v[206:209], v140 offset:3072
	v_lshl_add_u64 v[140:141], s[28:29], 0, v[0:1]
	s_mov_b32 m0, s84
	v_lshl_add_u64 v[212:213], s[28:29], 0, v[134:135]
	global_load_lds_dwordx4 v[140:141], off
	s_add_i32 m0, s84, 0x2000
	s_nop 0
	global_load_lds_dwordx4 v[212:213], off
	s_barrier
	s_waitcnt lgkmcnt(0)
	s_setprio 1
	s_waitcnt lgkmcnt(0)
	v_mfma_f32_16x16x32_bf16 v[122:125], v[194:197], v[162:165], v[122:125]
	v_mfma_f32_16x16x32_bf16 v[114:117], v[202:205], v[162:165], v[114:117]
	v_mfma_f32_16x16x32_bf16 v[106:109], v[194:197], v[170:173], v[106:109]
	v_mfma_f32_16x16x32_bf16 v[98:101], v[202:205], v[170:173], v[98:101]
	v_mfma_f32_16x16x32_bf16 v[90:93], v[194:197], v[178:181], v[90:93]
	v_mfma_f32_16x16x32_bf16 v[82:85], v[202:205], v[178:181], v[82:85]
	v_mfma_f32_16x16x32_bf16 v[74:77], v[194:197], v[186:189], v[74:77]
	v_mfma_f32_16x16x32_bf16 v[66:69], v[202:205], v[186:189], v[66:69]
	v_mfma_f32_16x16x32_bf16 v[122:125], v[198:201], v[166:169], v[122:125]
	v_mfma_f32_16x16x32_bf16 v[114:117], v[206:209], v[166:169], v[114:117]
	v_mfma_f32_16x16x32_bf16 v[106:109], v[198:201], v[174:177], v[106:109]
	v_mfma_f32_16x16x32_bf16 v[98:101], v[206:209], v[174:177], v[98:101]
	v_mfma_f32_16x16x32_bf16 v[90:93], v[198:201], v[182:185], v[90:93]
	v_mfma_f32_16x16x32_bf16 v[82:85], v[206:209], v[182:185], v[82:85]
	v_mfma_f32_16x16x32_bf16 v[74:77], v[198:201], v[190:193], v[74:77]
	v_mfma_f32_16x16x32_bf16 v[66:69], v[206:209], v[190:193], v[66:69]
	s_setprio 0
	s_mov_b32 m0, s19
	v_lshl_add_u64 v[214:215], s[34:35], 0, v[130:131]
	s_barrier
	ds_read_b128 v[162:165], v145 offset:16384
	ds_read_b128 v[166:169], v145 offset:17408
	ds_read_b128 v[170:173], v145 offset:18432
	ds_read_b128 v[174:177], v145 offset:19456
	ds_read_b128 v[178:181], v145 offset:20480
	ds_read_b128 v[182:185], v145 offset:21504
	ds_read_b128 v[186:189], v145 offset:22528
	ds_read_b128 v[190:193], v145 offset:23552
	global_load_lds_dwordx4 v[214:215], off
	v_lshl_add_u64 v[216:217], s[34:35], 0, v[132:133]
	s_mov_b32 m0, s21
	s_nop 0
	global_load_lds_dwordx4 v[216:217], off
	s_barrier
	s_waitcnt lgkmcnt(0)
	s_setprio 1
	s_waitcnt lgkmcnt(0)
	v_mfma_f32_16x16x32_bf16 v[62:65], v[146:149], v[162:165], v[62:65]
	v_mfma_f32_16x16x32_bf16 v[54:57], v[154:157], v[162:165], v[54:57]
	v_mfma_f32_16x16x32_bf16 v[46:49], v[146:149], v[170:173], v[46:49]
	v_mfma_f32_16x16x32_bf16 v[38:41], v[154:157], v[170:173], v[38:41]
	v_mfma_f32_16x16x32_bf16 v[30:33], v[146:149], v[178:181], v[30:33]
	v_mfma_f32_16x16x32_bf16 v[22:25], v[154:157], v[178:181], v[22:25]
	v_mfma_f32_16x16x32_bf16 v[14:17], v[146:149], v[186:189], v[14:17]
	v_mfma_f32_16x16x32_bf16 v[6:9], v[154:157], v[186:189], v[6:9]
	v_mfma_f32_16x16x32_bf16 v[62:65], v[150:153], v[166:169], v[62:65]
	v_mfma_f32_16x16x32_bf16 v[54:57], v[158:161], v[166:169], v[54:57]
	v_mfma_f32_16x16x32_bf16 v[46:49], v[150:153], v[174:177], v[46:49]
	v_mfma_f32_16x16x32_bf16 v[38:41], v[158:161], v[174:177], v[38:41]
	v_mfma_f32_16x16x32_bf16 v[30:33], v[150:153], v[182:185], v[30:33]
	v_mfma_f32_16x16x32_bf16 v[22:25], v[158:161], v[182:185], v[22:25]
	v_mfma_f32_16x16x32_bf16 v[14:17], v[150:153], v[190:193], v[14:17]
	v_mfma_f32_16x16x32_bf16 v[6:9], v[158:161], v[190:193], v[6:9]
	s_setprio 0
	s_barrier
	s_add_u32 s84, s28, 0x40000
	s_addc_u32 s85, s29, 0
	s_add_i32 s86, s86, s63
	v_lshl_add_u64 v[146:147], s[84:85], 0, v[0:1]
	s_mov_b32 m0, s86
	s_nop 0
	global_load_lds_dwordx4 v[146:147], off
	v_lshl_add_u64 v[146:147], s[84:85], 0, v[134:135]
	s_add_i32 m0, s86, 0x2000
	s_nop 0
	global_load_lds_dwordx4 v[146:147], off
	s_waitcnt vmcnt(6)
	s_barrier
	s_setprio 1
	v_mfma_f32_16x16x32_bf16 v[58:61], v[194:197], v[162:165], v[58:61]
	v_mfma_f32_16x16x32_bf16 v[50:53], v[202:205], v[162:165], v[50:53]
	v_mfma_f32_16x16x32_bf16 v[42:45], v[194:197], v[170:173], v[42:45]
	v_mfma_f32_16x16x32_bf16 v[34:37], v[202:205], v[170:173], v[34:37]
	v_mfma_f32_16x16x32_bf16 v[26:29], v[194:197], v[178:181], v[26:29]
	v_mfma_f32_16x16x32_bf16 v[18:21], v[202:205], v[178:181], v[18:21]
	v_mfma_f32_16x16x32_bf16 v[10:13], v[194:197], v[186:189], v[10:13]
	v_mfma_f32_16x16x32_bf16 v[2:5], v[202:205], v[186:189], v[2:5]
	v_mfma_f32_16x16x32_bf16 v[58:61], v[198:201], v[166:169], v[58:61]
	v_mfma_f32_16x16x32_bf16 v[50:53], v[206:209], v[166:169], v[50:53]
	v_mfma_f32_16x16x32_bf16 v[42:45], v[198:201], v[174:177], v[42:45]
	v_mfma_f32_16x16x32_bf16 v[34:37], v[206:209], v[174:177], v[34:37]
	v_mfma_f32_16x16x32_bf16 v[26:29], v[198:201], v[182:185], v[26:29]
	v_mfma_f32_16x16x32_bf16 v[18:21], v[206:209], v[182:185], v[18:21]
	v_mfma_f32_16x16x32_bf16 v[10:13], v[198:201], v[190:193], v[10:13]
	v_mfma_f32_16x16x32_bf16 v[2:5], v[206:209], v[190:193], v[2:5]
	s_setprio 0
	s_add_i32 s84, 0, 0x18000
	v_add_u32_e32 v158, s84, v143
	s_barrier
	ds_read_b128 v[146:149], v158
	ds_read_b128 v[150:153], v158 offset:1024
	ds_read_b128 v[154:157], v158 offset:2048
	ds_read_b128 v[158:161], v158 offset:3072
	s_add_u32 s34, s34, 0x40000
	s_addc_u32 s35, s35, 0
	s_mov_b32 m0, s64
	v_lshl_add_u64 v[194:195], s[34:35], 0, v[130:131]
	ds_read_b128 v[162:165], v145 offset:32768
	ds_read_b128 v[166:169], v145 offset:33792
	ds_read_b128 v[170:173], v145 offset:34816
	ds_read_b128 v[174:177], v145 offset:35840
	ds_read_b128 v[178:181], v145 offset:36864
	ds_read_b128 v[182:185], v145 offset:37888
	ds_read_b128 v[186:189], v145 offset:38912
	ds_read_b128 v[190:193], v145 offset:39936
	global_load_lds_dwordx4 v[194:195], off
	v_lshl_add_u64 v[194:195], s[34:35], 0, v[132:133]
	s_mov_b32 m0, s65
	s_nop 0
	global_load_lds_dwordx4 v[194:195], off
	s_waitcnt lgkmcnt(8)
	s_barrier
	s_waitcnt lgkmcnt(0)
	s_setprio 1
	s_waitcnt lgkmcnt(0)
	v_mfma_f32_16x16x32_bf16 v[126:129], v[146:149], v[162:165], v[126:129]
	v_mfma_f32_16x16x32_bf16 v[118:121], v[154:157], v[162:165], v[118:121]
	v_mfma_f32_16x16x32_bf16 v[110:113], v[146:149], v[170:173], v[110:113]
	v_mfma_f32_16x16x32_bf16 v[102:105], v[154:157], v[170:173], v[102:105]
	v_mfma_f32_16x16x32_bf16 v[94:97], v[146:149], v[178:181], v[94:97]
	v_mfma_f32_16x16x32_bf16 v[86:89], v[154:157], v[178:181], v[86:89]
	v_mfma_f32_16x16x32_bf16 v[78:81], v[146:149], v[186:189], v[78:81]
	v_mfma_f32_16x16x32_bf16 v[70:73], v[154:157], v[186:189], v[70:73]
	v_mfma_f32_16x16x32_bf16 v[126:129], v[150:153], v[166:169], v[126:129]
	v_mfma_f32_16x16x32_bf16 v[118:121], v[158:161], v[166:169], v[118:121]
	v_mfma_f32_16x16x32_bf16 v[110:113], v[150:153], v[174:177], v[110:113]
	v_mfma_f32_16x16x32_bf16 v[102:105], v[158:161], v[174:177], v[102:105]
	v_mfma_f32_16x16x32_bf16 v[94:97], v[150:153], v[182:185], v[94:97]
	v_mfma_f32_16x16x32_bf16 v[86:89], v[158:161], v[182:185], v[86:89]
	v_mfma_f32_16x16x32_bf16 v[78:81], v[150:153], v[190:193], v[78:81]
	v_mfma_f32_16x16x32_bf16 v[70:73], v[158:161], v[190:193], v[70:73]
	s_setprio 0
	s_barrier
	s_add_i32 s34, 0, 0x1c000
	s_add_i32 s35, s84, s63
	v_add_u32_e32 v206, s34, v143
	v_lshl_add_u64 v[140:141], v[140:141], 0, s[56:57]
	s_mov_b32 m0, s35
	ds_read_b128 v[194:197], v206
	ds_read_b128 v[198:201], v206 offset:1024
	ds_read_b128 v[202:205], v206 offset:2048
	ds_read_b128 v[206:209], v206 offset:3072
	global_load_lds_dwordx4 v[140:141], off
	v_lshl_add_u64 v[140:141], v[212:213], 0, s[56:57]
	s_add_i32 m0, s35, 0x2000
	s_nop 0
	global_load_lds_dwordx4 v[140:141], off
	s_barrier
	s_waitcnt lgkmcnt(0)
	s_setprio 1
	s_waitcnt lgkmcnt(0)
	v_mfma_f32_16x16x32_bf16 v[122:125], v[194:197], v[162:165], v[122:125]
	v_mfma_f32_16x16x32_bf16 v[114:117], v[202:205], v[162:165], v[114:117]
	v_mfma_f32_16x16x32_bf16 v[106:109], v[194:197], v[170:173], v[106:109]
	v_mfma_f32_16x16x32_bf16 v[98:101], v[202:205], v[170:173], v[98:101]
	v_mfma_f32_16x16x32_bf16 v[90:93], v[194:197], v[178:181], v[90:93]
	v_mfma_f32_16x16x32_bf16 v[82:85], v[202:205], v[178:181], v[82:85]
	v_mfma_f32_16x16x32_bf16 v[74:77], v[194:197], v[186:189], v[74:77]
	v_mfma_f32_16x16x32_bf16 v[66:69], v[202:205], v[186:189], v[66:69]
	v_mfma_f32_16x16x32_bf16 v[122:125], v[198:201], v[166:169], v[122:125]
	v_mfma_f32_16x16x32_bf16 v[114:117], v[206:209], v[166:169], v[114:117]
	v_mfma_f32_16x16x32_bf16 v[106:109], v[198:201], v[174:177], v[106:109]
	v_mfma_f32_16x16x32_bf16 v[98:101], v[206:209], v[174:177], v[98:101]
	v_mfma_f32_16x16x32_bf16 v[90:93], v[198:201], v[182:185], v[90:93]
	v_mfma_f32_16x16x32_bf16 v[82:85], v[206:209], v[182:185], v[82:85]
	v_mfma_f32_16x16x32_bf16 v[74:77], v[198:201], v[190:193], v[74:77]
	v_mfma_f32_16x16x32_bf16 v[66:69], v[206:209], v[190:193], v[66:69]
	s_setprio 0
	s_mov_b32 m0, s76
	v_lshl_add_u64 v[140:141], v[214:215], 0, s[56:57]
	s_barrier
	ds_read_b128 v[162:165], v145 offset:49152
	ds_read_b128 v[166:169], v145 offset:50176
	ds_read_b128 v[170:173], v145 offset:51200
	ds_read_b128 v[174:177], v145 offset:52224
	ds_read_b128 v[178:181], v145 offset:53248
	ds_read_b128 v[182:185], v145 offset:54272
	ds_read_b128 v[186:189], v145 offset:55296
	ds_read_b128 v[190:193], v145 offset:56320
	global_load_lds_dwordx4 v[140:141], off
	v_lshl_add_u64 v[140:141], v[216:217], 0, s[56:57]
	s_mov_b32 m0, s77
	s_nop 0
	global_load_lds_dwordx4 v[140:141], off
	s_barrier
	s_waitcnt lgkmcnt(0)
	s_setprio 1
	s_waitcnt lgkmcnt(0)
	v_mfma_f32_16x16x32_bf16 v[62:65], v[146:149], v[162:165], v[62:65]
	v_mfma_f32_16x16x32_bf16 v[54:57], v[154:157], v[162:165], v[54:57]
	v_mfma_f32_16x16x32_bf16 v[46:49], v[146:149], v[170:173], v[46:49]
	v_mfma_f32_16x16x32_bf16 v[38:41], v[154:157], v[170:173], v[38:41]
	v_mfma_f32_16x16x32_bf16 v[30:33], v[146:149], v[178:181], v[30:33]
	v_mfma_f32_16x16x32_bf16 v[22:25], v[154:157], v[178:181], v[22:25]
	v_mfma_f32_16x16x32_bf16 v[14:17], v[146:149], v[186:189], v[14:17]
	v_mfma_f32_16x16x32_bf16 v[6:9], v[154:157], v[186:189], v[6:9]
	v_mfma_f32_16x16x32_bf16 v[62:65], v[150:153], v[166:169], v[62:65]
	v_mfma_f32_16x16x32_bf16 v[54:57], v[158:161], v[166:169], v[54:57]
	v_mfma_f32_16x16x32_bf16 v[46:49], v[150:153], v[174:177], v[46:49]
	v_mfma_f32_16x16x32_bf16 v[38:41], v[158:161], v[174:177], v[38:41]
	v_mfma_f32_16x16x32_bf16 v[30:33], v[150:153], v[182:185], v[30:33]
	v_mfma_f32_16x16x32_bf16 v[22:25], v[158:161], v[182:185], v[22:25]
	v_mfma_f32_16x16x32_bf16 v[14:17], v[150:153], v[190:193], v[14:17]
	v_mfma_f32_16x16x32_bf16 v[6:9], v[158:161], v[190:193], v[6:9]
	s_setprio 0
	s_barrier
	s_add_u32 s28, s28, 0x40080
	s_addc_u32 s29, s29, 0
	s_add_i32 s34, s34, s63
	v_lshl_add_u64 v[140:141], s[28:29], 0, v[0:1]
	s_mov_b32 m0, s34
	s_nop 0
	global_load_lds_dwordx4 v[140:141], off
	v_lshl_add_u64 v[140:141], s[28:29], 0, v[134:135]
	s_add_i32 m0, s34, 0x2000
	s_nop 0
	global_load_lds_dwordx4 v[140:141], off
	s_waitcnt vmcnt(6)
	s_barrier
	s_setprio 1
	v_mfma_f32_16x16x32_bf16 v[58:61], v[194:197], v[162:165], v[58:61]
	v_mfma_f32_16x16x32_bf16 v[50:53], v[202:205], v[162:165], v[50:53]
	v_mfma_f32_16x16x32_bf16 v[42:45], v[194:197], v[170:173], v[42:45]
	v_mfma_f32_16x16x32_bf16 v[34:37], v[202:205], v[170:173], v[34:37]
	v_mfma_f32_16x16x32_bf16 v[26:29], v[194:197], v[178:181], v[26:29]
	v_mfma_f32_16x16x32_bf16 v[18:21], v[202:205], v[178:181], v[18:21]
	v_mfma_f32_16x16x32_bf16 v[10:13], v[194:197], v[186:189], v[10:13]
	v_mfma_f32_16x16x32_bf16 v[2:5], v[202:205], v[186:189], v[2:5]
	v_mfma_f32_16x16x32_bf16 v[58:61], v[198:201], v[166:169], v[58:61]
	v_mfma_f32_16x16x32_bf16 v[50:53], v[206:209], v[166:169], v[50:53]
	v_mfma_f32_16x16x32_bf16 v[42:45], v[198:201], v[174:177], v[42:45]
	v_mfma_f32_16x16x32_bf16 v[34:37], v[206:209], v[174:177], v[34:37]
	v_mfma_f32_16x16x32_bf16 v[26:29], v[198:201], v[182:185], v[26:29]
	v_mfma_f32_16x16x32_bf16 v[18:21], v[206:209], v[182:185], v[18:21]
	v_mfma_f32_16x16x32_bf16 v[10:13], v[198:201], v[190:193], v[10:13]
	v_mfma_f32_16x16x32_bf16 v[2:5], v[206:209], v[190:193], v[2:5]
	s_setprio 0
	s_add_i32 s83, s83, 2
	s_add_u32 s22, s22, 0x100
	s_addc_u32 s23, s23, 0
	s_add_u32 s81, s81, 0x100
	s_addc_u32 s82, s82, 0
	s_cmp_gt_u32 s83, 13
	s_barrier
	s_cbranch_scc0 .LBB0_1206
	v_readlane_b32 s80, v254, 55
	v_lshl_or_b32 v148, s18, 7, v144
	v_readlane_b32 s81, v254, 56
	v_lshl_add_u32 v146, s20, 8, v142
	v_ashrrev_i32_e32 v149, 31, v148
	s_movk_i32 s11, 0x1600
	s_and_b64 vcc, exec, s[0:1]
	s_mov_b32 s18, s10
	s_mov_b32 s20, s12
	s_mov_b64 s[34:35], s[16:17]
	v_lshlrev_b64 v[148:149], 1, v[148:149]
	v_mov_b64_e32 v[140:141], s[80:81]
	v_lshl_add_u64 v[150:151], v[140:141], 0, v[148:149]
	v_mul_f32_e32 v152, 0xbfb8aa3b, v126
	v_mul_f32_e32 v153, 0xbfb8aa3b, v127
	v_mul_f32_e32 v154, 0xbfb8aa3b, v128
	v_mul_f32_e32 v155, 0xbfb8aa3b, v129
	v_mul_f32_e32 v156, 0xbfb8aa3b, v118
	v_mul_f32_e32 v157, 0xbfb8aa3b, v119
	v_mul_f32_e32 v158, 0xbfb8aa3b, v120
	v_mul_f32_e32 v159, 0xbfb8aa3b, v121
	v_exp_f32_e32 v152, v152
	v_exp_f32_e32 v153, v153
	v_exp_f32_e32 v154, v154
	v_exp_f32_e32 v155, v155
	v_exp_f32_e32 v156, v156
	v_exp_f32_e32 v157, v157
	v_exp_f32_e32 v158, v158
	v_exp_f32_e32 v159, v159
	v_mov_b32_e32 v166, v146
	v_mad_i64_i32 v[164:165], s[22:23], v166, s11, v[150:151]
	v_add_f32_e32 v152, 1.0, v152
	v_add_f32_e32 v153, 1.0, v153
	v_add_f32_e32 v154, 1.0, v154
	v_add_f32_e32 v155, 1.0, v155
	v_add_f32_e32 v156, 1.0, v156
	v_add_f32_e32 v157, 1.0, v157
	v_add_f32_e32 v158, 1.0, v158
	v_add_f32_e32 v159, 1.0, v159
	v_rcp_f32_e32 v152, v152
	v_rcp_f32_e32 v153, v153
	v_rcp_f32_e32 v154, v154
	v_rcp_f32_e32 v155, v155
	v_rcp_f32_e32 v156, v156
	v_rcp_f32_e32 v157, v157
	v_rcp_f32_e32 v158, v158
	v_rcp_f32_e32 v159, v159
	s_nop 0
	v_mul_f32_e32 v126, v126, v152
	v_mul_f32_e32 v127, v127, v153
	v_mul_f32_e32 v128, v128, v154
	v_mul_f32_e32 v129, v129, v155
	v_mul_f32_e32 v118, v118, v156
	v_mul_f32_e32 v119, v119, v157
	v_mul_f32_e32 v120, v120, v158
	v_mul_f32_e32 v121, v121, v159
	v_mul_f32_e32 v126, v126, v122
	v_mul_f32_e32 v127, v127, v123
	v_mul_f32_e32 v128, v128, v124
	v_mul_f32_e32 v129, v129, v125
	v_mul_f32_e32 v118, v118, v114
	v_mul_f32_e32 v119, v119, v115
	v_mul_f32_e32 v120, v120, v116
	v_mul_f32_e32 v121, v121, v117
	v_cvt_pk_bf16_f32 v160, v126, v127
	v_cvt_pk_bf16_f32 v161, v128, v129
	v_cvt_pk_bf16_f32 v162, v118, v119
	v_cvt_pk_bf16_f32 v163, v120, v121
	global_store_dwordx4 v[164:165], v[160:163], off
	v_mul_f32_e32 v152, 0xbfb8aa3b, v110
	v_mul_f32_e32 v153, 0xbfb8aa3b, v111
	v_mul_f32_e32 v154, 0xbfb8aa3b, v112
	v_mul_f32_e32 v155, 0xbfb8aa3b, v113
	v_mul_f32_e32 v156, 0xbfb8aa3b, v102
	v_mul_f32_e32 v157, 0xbfb8aa3b, v103
	v_mul_f32_e32 v158, 0xbfb8aa3b, v104
	v_mul_f32_e32 v159, 0xbfb8aa3b, v105
	v_exp_f32_e32 v152, v152
	v_exp_f32_e32 v153, v153
	v_exp_f32_e32 v154, v154
	v_exp_f32_e32 v155, v155
	v_exp_f32_e32 v156, v156
	v_exp_f32_e32 v157, v157
	v_exp_f32_e32 v158, v158
	v_exp_f32_e32 v159, v159
	v_add_u32_e32 v166, 16, v146
	v_mad_i64_i32 v[164:165], s[22:23], v166, s11, v[150:151]
	v_add_f32_e32 v152, 1.0, v152
	v_add_f32_e32 v153, 1.0, v153
	v_add_f32_e32 v154, 1.0, v154
	v_add_f32_e32 v155, 1.0, v155
	v_add_f32_e32 v156, 1.0, v156
	v_add_f32_e32 v157, 1.0, v157
	v_add_f32_e32 v158, 1.0, v158
	v_add_f32_e32 v159, 1.0, v159
	v_rcp_f32_e32 v152, v152
	v_rcp_f32_e32 v153, v153
	v_rcp_f32_e32 v154, v154
	v_rcp_f32_e32 v155, v155
	v_rcp_f32_e32 v156, v156
	v_rcp_f32_e32 v157, v157
	v_rcp_f32_e32 v158, v158
	v_rcp_f32_e32 v159, v159
	s_nop 0
	v_mul_f32_e32 v110, v110, v152
	v_mul_f32_e32 v111, v111, v153
	v_mul_f32_e32 v112, v112, v154
	v_mul_f32_e32 v113, v113, v155
	v_mul_f32_e32 v102, v102, v156
	v_mul_f32_e32 v103, v103, v157
	v_mul_f32_e32 v104, v104, v158
	v_mul_f32_e32 v105, v105, v159
	v_mul_f32_e32 v110, v110, v106
	v_mul_f32_e32 v111, v111, v107
	v_mul_f32_e32 v112, v112, v108
	v_mul_f32_e32 v113, v113, v109
	v_mul_f32_e32 v102, v102, v98
	v_mul_f32_e32 v103, v103, v99
	v_mul_f32_e32 v104, v104, v100
	v_mul_f32_e32 v105, v105, v101
	v_cvt_pk_bf16_f32 v160, v110, v111
	v_cvt_pk_bf16_f32 v161, v112, v113
	v_cvt_pk_bf16_f32 v162, v102, v103
	v_cvt_pk_bf16_f32 v163, v104, v105
	global_store_dwordx4 v[164:165], v[160:163], off
	v_mul_f32_e32 v152, 0xbfb8aa3b, v94
	v_mul_f32_e32 v153, 0xbfb8aa3b, v95
	v_mul_f32_e32 v154, 0xbfb8aa3b, v96
	v_mul_f32_e32 v155, 0xbfb8aa3b, v97
	v_mul_f32_e32 v156, 0xbfb8aa3b, v86
	v_mul_f32_e32 v157, 0xbfb8aa3b, v87
	v_mul_f32_e32 v158, 0xbfb8aa3b, v88
	v_mul_f32_e32 v159, 0xbfb8aa3b, v89
	v_exp_f32_e32 v152, v152
	v_exp_f32_e32 v153, v153
	v_exp_f32_e32 v154, v154
	v_exp_f32_e32 v155, v155
	v_exp_f32_e32 v156, v156
	v_exp_f32_e32 v157, v157
	v_exp_f32_e32 v158, v158
	v_exp_f32_e32 v159, v159
	v_add_u32_e32 v166, 32, v146
	v_mad_i64_i32 v[164:165], s[22:23], v166, s11, v[150:151]
	v_add_f32_e32 v152, 1.0, v152
	v_add_f32_e32 v153, 1.0, v153
	v_add_f32_e32 v154, 1.0, v154
	v_add_f32_e32 v155, 1.0, v155
	v_add_f32_e32 v156, 1.0, v156
	v_add_f32_e32 v157, 1.0, v157
	v_add_f32_e32 v158, 1.0, v158
	v_add_f32_e32 v159, 1.0, v159
	v_rcp_f32_e32 v152, v152
	v_rcp_f32_e32 v153, v153
	v_rcp_f32_e32 v154, v154
	v_rcp_f32_e32 v155, v155
	v_rcp_f32_e32 v156, v156
	v_rcp_f32_e32 v157, v157
	v_rcp_f32_e32 v158, v158
	v_rcp_f32_e32 v159, v159
	s_nop 0
	v_mul_f32_e32 v94, v94, v152
	v_mul_f32_e32 v95, v95, v153
	v_mul_f32_e32 v96, v96, v154
	v_mul_f32_e32 v97, v97, v155
	v_mul_f32_e32 v86, v86, v156
	v_mul_f32_e32 v87, v87, v157
	v_mul_f32_e32 v88, v88, v158
	v_mul_f32_e32 v89, v89, v159
	v_mul_f32_e32 v94, v94, v90
	v_mul_f32_e32 v95, v95, v91
	v_mul_f32_e32 v96, v96, v92
	v_mul_f32_e32 v97, v97, v93
	v_mul_f32_e32 v86, v86, v82
	v_mul_f32_e32 v87, v87, v83
	v_mul_f32_e32 v88, v88, v84
	v_mul_f32_e32 v89, v89, v85
	v_cvt_pk_bf16_f32 v160, v94, v95
	v_cvt_pk_bf16_f32 v161, v96, v97
	v_cvt_pk_bf16_f32 v162, v86, v87
	v_cvt_pk_bf16_f32 v163, v88, v89
	global_store_dwordx4 v[164:165], v[160:163], off
	v_mul_f32_e32 v152, 0xbfb8aa3b, v78
	v_mul_f32_e32 v153, 0xbfb8aa3b, v79
	v_mul_f32_e32 v154, 0xbfb8aa3b, v80
	v_mul_f32_e32 v155, 0xbfb8aa3b, v81
	v_mul_f32_e32 v156, 0xbfb8aa3b, v70
	v_mul_f32_e32 v157, 0xbfb8aa3b, v71
	v_mul_f32_e32 v158, 0xbfb8aa3b, v72
	v_mul_f32_e32 v159, 0xbfb8aa3b, v73
	v_exp_f32_e32 v152, v152
	v_exp_f32_e32 v153, v153
	v_exp_f32_e32 v154, v154
	v_exp_f32_e32 v155, v155
	v_exp_f32_e32 v156, v156
	v_exp_f32_e32 v157, v157
	v_exp_f32_e32 v158, v158
	v_exp_f32_e32 v159, v159
	v_add_u32_e32 v166, 48, v146
	v_mad_i64_i32 v[164:165], s[22:23], v166, s11, v[150:151]
	v_add_f32_e32 v152, 1.0, v152
	v_add_f32_e32 v153, 1.0, v153
	v_add_f32_e32 v154, 1.0, v154
	v_add_f32_e32 v155, 1.0, v155
	v_add_f32_e32 v156, 1.0, v156
	v_add_f32_e32 v157, 1.0, v157
	v_add_f32_e32 v158, 1.0, v158
	v_add_f32_e32 v159, 1.0, v159
	v_rcp_f32_e32 v152, v152
	v_rcp_f32_e32 v153, v153
	v_rcp_f32_e32 v154, v154
	v_rcp_f32_e32 v155, v155
	v_rcp_f32_e32 v156, v156
	v_rcp_f32_e32 v157, v157
	v_rcp_f32_e32 v158, v158
	v_rcp_f32_e32 v159, v159
	s_nop 0
	v_mul_f32_e32 v78, v78, v152
	v_mul_f32_e32 v79, v79, v153
	v_mul_f32_e32 v80, v80, v154
	v_mul_f32_e32 v81, v81, v155
	v_mul_f32_e32 v70, v70, v156
	v_mul_f32_e32 v71, v71, v157
	v_mul_f32_e32 v72, v72, v158
	v_mul_f32_e32 v73, v73, v159
	v_mul_f32_e32 v78, v78, v74
	v_mul_f32_e32 v79, v79, v75
	v_mul_f32_e32 v80, v80, v76
	v_mul_f32_e32 v81, v81, v77
	v_mul_f32_e32 v70, v70, v66
	v_mul_f32_e32 v71, v71, v67
	v_mul_f32_e32 v72, v72, v68
	v_mul_f32_e32 v73, v73, v69
	v_cvt_pk_bf16_f32 v160, v78, v79
	v_cvt_pk_bf16_f32 v161, v80, v81
	v_cvt_pk_bf16_f32 v162, v70, v71
	v_cvt_pk_bf16_f32 v163, v72, v73
	global_store_dwordx4 v[164:165], v[160:163], off
	v_mul_f32_e32 v152, 0xbfb8aa3b, v62
	v_mul_f32_e32 v153, 0xbfb8aa3b, v63
	v_mul_f32_e32 v154, 0xbfb8aa3b, v64
	v_mul_f32_e32 v155, 0xbfb8aa3b, v65
	v_mul_f32_e32 v156, 0xbfb8aa3b, v54
	v_mul_f32_e32 v157, 0xbfb8aa3b, v55
	v_mul_f32_e32 v158, 0xbfb8aa3b, v56
	v_mul_f32_e32 v159, 0xbfb8aa3b, v57
	v_exp_f32_e32 v152, v152
	v_exp_f32_e32 v153, v153
	v_exp_f32_e32 v154, v154
	v_exp_f32_e32 v155, v155
	v_exp_f32_e32 v156, v156
	v_exp_f32_e32 v157, v157
	v_exp_f32_e32 v158, v158
	v_exp_f32_e32 v159, v159
	v_add_u32_e32 v166, 128, v146
	v_mad_i64_i32 v[164:165], s[22:23], v166, s11, v[150:151]
	v_add_f32_e32 v152, 1.0, v152
	v_add_f32_e32 v153, 1.0, v153
	v_add_f32_e32 v154, 1.0, v154
	v_add_f32_e32 v155, 1.0, v155
	v_add_f32_e32 v156, 1.0, v156
	v_add_f32_e32 v157, 1.0, v157
	v_add_f32_e32 v158, 1.0, v158
	v_add_f32_e32 v159, 1.0, v159
	v_rcp_f32_e32 v152, v152
	v_rcp_f32_e32 v153, v153
	v_rcp_f32_e32 v154, v154
	v_rcp_f32_e32 v155, v155
	v_rcp_f32_e32 v156, v156
	v_rcp_f32_e32 v157, v157
	v_rcp_f32_e32 v158, v158
	v_rcp_f32_e32 v159, v159
	s_nop 0
	v_mul_f32_e32 v62, v62, v152
	v_mul_f32_e32 v63, v63, v153
	v_mul_f32_e32 v64, v64, v154
	v_mul_f32_e32 v65, v65, v155
	v_mul_f32_e32 v54, v54, v156
	v_mul_f32_e32 v55, v55, v157
	v_mul_f32_e32 v56, v56, v158
	v_mul_f32_e32 v57, v57, v159
	v_mul_f32_e32 v62, v62, v58
	v_mul_f32_e32 v63, v63, v59
	v_mul_f32_e32 v64, v64, v60
	v_mul_f32_e32 v65, v65, v61
	v_mul_f32_e32 v54, v54, v50
	v_mul_f32_e32 v55, v55, v51
	v_mul_f32_e32 v56, v56, v52
	v_mul_f32_e32 v57, v57, v53
	v_cvt_pk_bf16_f32 v160, v62, v63
	v_cvt_pk_bf16_f32 v161, v64, v65
	v_cvt_pk_bf16_f32 v162, v54, v55
	v_cvt_pk_bf16_f32 v163, v56, v57
	global_store_dwordx4 v[164:165], v[160:163], off
	v_mul_f32_e32 v152, 0xbfb8aa3b, v46
	v_mul_f32_e32 v153, 0xbfb8aa3b, v47
	v_mul_f32_e32 v154, 0xbfb8aa3b, v48
	v_mul_f32_e32 v155, 0xbfb8aa3b, v49
	v_mul_f32_e32 v156, 0xbfb8aa3b, v38
	v_mul_f32_e32 v157, 0xbfb8aa3b, v39
	v_mul_f32_e32 v158, 0xbfb8aa3b, v40
	v_mul_f32_e32 v159, 0xbfb8aa3b, v41
	v_exp_f32_e32 v152, v152
	v_exp_f32_e32 v153, v153
	v_exp_f32_e32 v154, v154
	v_exp_f32_e32 v155, v155
	v_exp_f32_e32 v156, v156
	v_exp_f32_e32 v157, v157
	v_exp_f32_e32 v158, v158
	v_exp_f32_e32 v159, v159
	v_add_u32_e32 v166, 144, v146
	v_mad_i64_i32 v[164:165], s[22:23], v166, s11, v[150:151]
	v_add_f32_e32 v152, 1.0, v152
	v_add_f32_e32 v153, 1.0, v153
	v_add_f32_e32 v154, 1.0, v154
	v_add_f32_e32 v155, 1.0, v155
	v_add_f32_e32 v156, 1.0, v156
	v_add_f32_e32 v157, 1.0, v157
	v_add_f32_e32 v158, 1.0, v158
	v_add_f32_e32 v159, 1.0, v159
	v_rcp_f32_e32 v152, v152
	v_rcp_f32_e32 v153, v153
	v_rcp_f32_e32 v154, v154
	v_rcp_f32_e32 v155, v155
	v_rcp_f32_e32 v156, v156
	v_rcp_f32_e32 v157, v157
	v_rcp_f32_e32 v158, v158
	v_rcp_f32_e32 v159, v159
	s_nop 0
	v_mul_f32_e32 v46, v46, v152
	v_mul_f32_e32 v47, v47, v153
	v_mul_f32_e32 v48, v48, v154
	v_mul_f32_e32 v49, v49, v155
	v_mul_f32_e32 v38, v38, v156
	v_mul_f32_e32 v39, v39, v157
	v_mul_f32_e32 v40, v40, v158
	v_mul_f32_e32 v41, v41, v159
	v_mul_f32_e32 v46, v46, v42
	v_mul_f32_e32 v47, v47, v43
	v_mul_f32_e32 v48, v48, v44
	v_mul_f32_e32 v49, v49, v45
	v_mul_f32_e32 v38, v38, v34
	v_mul_f32_e32 v39, v39, v35
	v_mul_f32_e32 v40, v40, v36
	v_mul_f32_e32 v41, v41, v37
	v_cvt_pk_bf16_f32 v160, v46, v47
	v_cvt_pk_bf16_f32 v161, v48, v49
	v_cvt_pk_bf16_f32 v162, v38, v39
	v_cvt_pk_bf16_f32 v163, v40, v41
	global_store_dwordx4 v[164:165], v[160:163], off
	v_mul_f32_e32 v152, 0xbfb8aa3b, v30
	v_mul_f32_e32 v153, 0xbfb8aa3b, v31
	v_mul_f32_e32 v154, 0xbfb8aa3b, v32
	v_mul_f32_e32 v155, 0xbfb8aa3b, v33
	v_mul_f32_e32 v156, 0xbfb8aa3b, v22
	v_mul_f32_e32 v157, 0xbfb8aa3b, v23
	v_mul_f32_e32 v158, 0xbfb8aa3b, v24
	v_mul_f32_e32 v159, 0xbfb8aa3b, v25
	v_exp_f32_e32 v152, v152
	v_exp_f32_e32 v153, v153
	v_exp_f32_e32 v154, v154
	v_exp_f32_e32 v155, v155
	v_exp_f32_e32 v156, v156
	v_exp_f32_e32 v157, v157
	v_exp_f32_e32 v158, v158
	v_exp_f32_e32 v159, v159
	v_add_u32_e32 v166, 160, v146
	v_mad_i64_i32 v[164:165], s[22:23], v166, s11, v[150:151]
	v_add_f32_e32 v152, 1.0, v152
	v_add_f32_e32 v153, 1.0, v153
	v_add_f32_e32 v154, 1.0, v154
	v_add_f32_e32 v155, 1.0, v155
	v_add_f32_e32 v156, 1.0, v156
	v_add_f32_e32 v157, 1.0, v157
	v_add_f32_e32 v158, 1.0, v158
	v_add_f32_e32 v159, 1.0, v159
	v_rcp_f32_e32 v152, v152
	v_rcp_f32_e32 v153, v153
	v_rcp_f32_e32 v154, v154
	v_rcp_f32_e32 v155, v155
	v_rcp_f32_e32 v156, v156
	v_rcp_f32_e32 v157, v157
	v_rcp_f32_e32 v158, v158
	v_rcp_f32_e32 v159, v159
	s_nop 0
	v_mul_f32_e32 v30, v30, v152
	v_mul_f32_e32 v31, v31, v153
	v_mul_f32_e32 v32, v32, v154
	v_mul_f32_e32 v33, v33, v155
	v_mul_f32_e32 v22, v22, v156
	v_mul_f32_e32 v23, v23, v157
	v_mul_f32_e32 v24, v24, v158
	v_mul_f32_e32 v25, v25, v159
	v_mul_f32_e32 v30, v30, v26
	v_mul_f32_e32 v31, v31, v27
	v_mul_f32_e32 v32, v32, v28
	v_mul_f32_e32 v33, v33, v29
	v_mul_f32_e32 v22, v22, v18
	v_mul_f32_e32 v23, v23, v19
	v_mul_f32_e32 v24, v24, v20
	v_mul_f32_e32 v25, v25, v21
	v_cvt_pk_bf16_f32 v160, v30, v31
	v_cvt_pk_bf16_f32 v161, v32, v33
	v_cvt_pk_bf16_f32 v162, v22, v23
	v_cvt_pk_bf16_f32 v163, v24, v25
	global_store_dwordx4 v[164:165], v[160:163], off
	v_mul_f32_e32 v152, 0xbfb8aa3b, v14
	v_mul_f32_e32 v153, 0xbfb8aa3b, v15
	v_mul_f32_e32 v154, 0xbfb8aa3b, v16
	v_mul_f32_e32 v155, 0xbfb8aa3b, v17
	v_mul_f32_e32 v156, 0xbfb8aa3b, v6
	v_mul_f32_e32 v157, 0xbfb8aa3b, v7
	v_mul_f32_e32 v158, 0xbfb8aa3b, v8
	v_mul_f32_e32 v159, 0xbfb8aa3b, v9
	v_exp_f32_e32 v152, v152
	v_exp_f32_e32 v153, v153
	v_exp_f32_e32 v154, v154
	v_exp_f32_e32 v155, v155
	v_exp_f32_e32 v156, v156
	v_exp_f32_e32 v157, v157
	v_exp_f32_e32 v158, v158
	v_exp_f32_e32 v159, v159
	v_add_u32_e32 v166, 176, v146
	v_mad_i64_i32 v[164:165], s[22:23], v166, s11, v[150:151]
	v_add_f32_e32 v152, 1.0, v152
	v_add_f32_e32 v153, 1.0, v153
	v_add_f32_e32 v154, 1.0, v154
	v_add_f32_e32 v155, 1.0, v155
	v_add_f32_e32 v156, 1.0, v156
	v_add_f32_e32 v157, 1.0, v157
	v_add_f32_e32 v158, 1.0, v158
	v_add_f32_e32 v159, 1.0, v159
	v_rcp_f32_e32 v152, v152
	v_rcp_f32_e32 v153, v153
	v_rcp_f32_e32 v154, v154
	v_rcp_f32_e32 v155, v155
	v_rcp_f32_e32 v156, v156
	v_rcp_f32_e32 v157, v157
	v_rcp_f32_e32 v158, v158
	v_rcp_f32_e32 v159, v159
	s_mov_b64 s[22:23], s[14:15]
	v_mul_f32_e32 v14, v14, v152
	v_mul_f32_e32 v15, v15, v153
	v_mul_f32_e32 v16, v16, v154
	v_mul_f32_e32 v17, v17, v155
	v_mul_f32_e32 v6, v6, v156
	v_mul_f32_e32 v7, v7, v157
	v_mul_f32_e32 v8, v8, v158
	v_mul_f32_e32 v9, v9, v159
	v_mul_f32_e32 v14, v14, v10
	v_mul_f32_e32 v15, v15, v11
	v_mul_f32_e32 v16, v16, v12
	v_mul_f32_e32 v17, v17, v13
	v_mul_f32_e32 v6, v6, v2
	v_mul_f32_e32 v7, v7, v3
	v_mul_f32_e32 v8, v8, v4
	v_mul_f32_e32 v9, v9, v5
	v_cvt_pk_bf16_f32 v160, v14, v15
	v_cvt_pk_bf16_f32 v161, v16, v17
	v_cvt_pk_bf16_f32 v162, v6, v7
	v_cvt_pk_bf16_f32 v163, v8, v9
	global_store_dwordx4 v[164:165], v[160:163], off
	s_cbranch_vccz .LBB0_1202
	s_waitcnt vmcnt(0)
	s_cmpk_gt_u32 s24, 0xff
	s_cbranch_scc1 .LBB0_1210
	s_barrier
